# GLA scan output block: 4-deep LDS fragment ring + pre-combined row addresses (1 add per store)
# speedup vs baseline: 1.0111x; 1.0058x over previous
.LBB0_470:
	s_or_b64 exec, exec, s[4:5]
	s_lshr_b32 s86, s77, 2
	s_lshr_b32 s87, s77, 3
	s_and_b64 s[4:5], s[48:49], exec
	s_cselect_b32 s84, s68, 0x36c00000
	s_cselect_b32 s4, 0xc0, s67
	s_add_u32 s84, s94, s84
	s_addc_u32 s85, s95, 0
	s_lshl_b32 s10, s10, 1
	s_add_u32 s10, s84, s10
	s_addc_u32 s85, s85, 0
	s_mov_b32 s5, s11
	s_add_u32 s84, s10, s53
	s_addc_u32 s85, s85, 0
	s_or_b64 s[4:5], s[4:5], s[46:47]
	v_lshl_add_u64 v[10:11], s[4:5], 0, v[10:11]
	v_lshlrev_b64 v[10:11], 11, v[10:11]
	v_lshl_add_u64 v[10:11], v[146:147], 0, v[10:11]
	global_load_dwordx4 v[140:143], v[10:11], off
	v_lshlrev_b32_e32 v12, 5, v9
	v_and_b32_e32 v19, 32, v12
	v_and_b32_e32 v17, 31, v20
	v_lshlrev_b32_e32 v12, 1, v19
	v_mov_b32_e32 v13, v145
	v_lshl_add_u64 v[12:13], s[84:85], 0, v[12:13]
	v_lshlrev_b32_e32 v14, 1, v17
	v_mov_b32_e32 v15, v145
	v_lshl_add_u64 v[150:151], v[12:13], 0, v[14:15]
	v_mul_lo_u32 v12, v0, s69
	v_mul_lo_u32 v13, v21, s74
	v_ashrrev_i32_e32 v18, 7, v20
	v_add_u32_e32 v12, 0, v12
	v_add3_u32 v203, 0, v13, v8
	v_lshlrev_b32_e32 v8, 7, v0
	v_lshlrev_b32_e32 v16, 3, v23
	v_sub_u32_e32 v8, v12, v8
	v_lshlrev_b32_e32 v11, 5, v18
	v_lshl_add_u32 v202, v144, 1, v12
	v_lshl_add_u32 v204, v16, 1, v8
	v_lshrrev_b32_e32 v8, 5, v22
	v_and_b32_e32 v12, 32, v11
	v_lshlrev_b32_e32 v15, 3, v8
	v_lshlrev_b32_e32 v16, 4, v8
	v_lshl_or_b32 v8, v8, 2, v12
	v_mad_i32_i24 v154, v8, s52, s52
	v_add_u32_e32 v156, s52, v154
	v_add_u32_e32 v158, s52, v156
	v_mad_i32_i24 v160, s52, 5, v158
	v_add_u32_e32 v162, s52, v160
	v_add_u32_e32 v164, s52, v162
	v_add_u32_e32 v166, s52, v164
	v_mad_i32_i24 v168, s52, 5, v166
	s_and_b32 s10, s86, 1
	s_and_b32 s84, s87, 3
	v_add_u32_e32 v170, s52, v168
	s_lshl_b32 s53, s10, 5
	s_lshl_b32 s10, s10, 15
	s_lshl_b32 s85, s84, 8
	v_add_u32_e32 v172, s52, v170
	v_or_b32_e32 v13, v12, v17
	v_add_u32_e32 v174, s52, v172
	s_add_u32 s50, s53, s50
	v_mul_u32_u24_e32 v14, 0x110, v13
	v_mad_i32_i24 v176, s52, 5, v174
	s_addc_u32 s51, 0, s51
	v_add3_u32 v206, 0, v14, v16
	v_or_b32_e32 v14, v19, v17
	v_add_u32_e32 v178, s52, v176
	s_add_u32 s50, s50, s84
	v_mad_u32_u24 v19, v14, s69, 0
	v_lshlrev_b32_e32 v13, 7, v13
	v_add_u32_e32 v180, s52, v178
	s_addc_u32 s51, s51, 0
	v_add_u32_e32 v207, v19, v16
	v_sub_u32_e32 v209, v206, v13
	v_lshlrev_b32_e32 v13, 7, v14
	v_mul_i32_i24_e32 v152, s52, v8
	v_add_u32_e32 v182, s52, v180
	s_lshl_b64 s[52:53], s[50:51], 19
	v_cmp_gt_i32_e64 s[4:5], 4, v9
	v_sub_u32_e32 v210, v207, v13
	v_mul_lo_u32 v13, v9, s76
	v_mov_b32_e32 v9, s53
	v_or_b32_e32 v8, s52, v144
	v_lshl_add_u64 v[184:185], v[6:7], 1, v[8:9]
	s_lshl_b64 s[52:53], s[50:51], 20
	v_and_b32_e32 v6, 3, v20
	v_lshl_or_b32 v6, v6, 5, s52
	s_add_u32 s52, s10, s46
	v_or_b32_e32 v11, v11, v17
	v_mov_b32_e32 v7, s53
	s_addc_u32 s53, 0, s47
	s_lshl_b64 s[50:51], s[50:51], 15
	s_waitcnt lgkmcnt(0)
	s_barrier
	v_and_b32_e32 v12, 0xffffff80, v20
	v_mul_lo_u32 v11, v11, s74
	v_lshl_add_u64 v[0:1], s[52:53], 0, v[0:1]
	s_add_u32 s10, s50, 0x3ec00c00
	v_lshl_add_u32 v10, v22, 1, 0
	v_add_u32_e32 v12, s75, v12
	v_add3_u32 v211, 0, v11, v16
	v_lshl_add_u32 v11, v18, 6, v19
	v_lshlrev_b64 v[188:189], 10, v[0:1]
	s_addc_u32 s50, s51, 0
	v_mov_b32_e32 v0, 0
	v_lshl_add_u32 v205, v20, 2, s75
	v_ashrrev_i32_e32 v153, 31, v152
	v_ashrrev_i32_e32 v155, 31, v154
	v_ashrrev_i32_e32 v157, 31, v156
	v_ashrrev_i32_e32 v159, 31, v158
	v_ashrrev_i32_e32 v161, 31, v160
	v_ashrrev_i32_e32 v163, 31, v162
	v_ashrrev_i32_e32 v165, 31, v164
	v_ashrrev_i32_e32 v167, 31, v166
	v_ashrrev_i32_e32 v169, 31, v168
	v_ashrrev_i32_e32 v171, 31, v170
	v_ashrrev_i32_e32 v173, 31, v172
	v_ashrrev_i32_e32 v175, 31, v174
	v_ashrrev_i32_e32 v177, 31, v176
	v_ashrrev_i32_e32 v179, 31, v178
	v_ashrrev_i32_e32 v181, 31, v180
	v_ashrrev_i32_e32 v183, 31, v182
	v_lshlrev_b64 v[152:153], 11, v[152:153]
	v_lshl_add_u64 v[152:153], v[150:151], 0, v[152:153]
	v_lshlrev_b64 v[154:155], 11, v[154:155]
	v_lshl_add_u64 v[154:155], v[150:151], 0, v[154:155]
	v_lshlrev_b64 v[156:157], 11, v[156:157]
	v_lshl_add_u64 v[156:157], v[150:151], 0, v[156:157]
	v_lshlrev_b64 v[158:159], 11, v[158:159]
	v_lshl_add_u64 v[158:159], v[150:151], 0, v[158:159]
	v_lshlrev_b64 v[160:161], 11, v[160:161]
	v_lshl_add_u64 v[160:161], v[150:151], 0, v[160:161]
	v_lshlrev_b64 v[162:163], 11, v[162:163]
	v_lshl_add_u64 v[162:163], v[150:151], 0, v[162:163]
	v_lshlrev_b64 v[164:165], 11, v[164:165]
	v_lshl_add_u64 v[164:165], v[150:151], 0, v[164:165]
	v_lshlrev_b64 v[166:167], 11, v[166:167]
	v_lshl_add_u64 v[166:167], v[150:151], 0, v[166:167]
	v_lshlrev_b64 v[168:169], 11, v[168:169]
	v_lshl_add_u64 v[168:169], v[150:151], 0, v[168:169]
	v_lshlrev_b64 v[170:171], 11, v[170:171]
	v_lshl_add_u64 v[170:171], v[150:151], 0, v[170:171]
	v_lshlrev_b64 v[172:173], 11, v[172:173]
	v_lshl_add_u64 v[172:173], v[150:151], 0, v[172:173]
	v_lshlrev_b64 v[174:175], 11, v[174:175]
	v_lshl_add_u64 v[174:175], v[150:151], 0, v[174:175]
	v_lshlrev_b64 v[176:177], 11, v[176:177]
	v_lshl_add_u64 v[176:177], v[150:151], 0, v[176:177]
	v_lshlrev_b64 v[178:179], 11, v[178:179]
	v_lshl_add_u64 v[178:179], v[150:151], 0, v[178:179]
	v_lshlrev_b64 v[180:181], 11, v[180:181]
	v_lshl_add_u64 v[180:181], v[150:151], 0, v[180:181]
	v_lshlrev_b64 v[182:183], 11, v[182:183]
	v_lshl_add_u64 v[182:183], v[150:151], 0, v[182:183]
	v_lshl_add_u64 v[186:187], v[4:5], 1, v[6:7]
	v_or3_b32 v188, v188, s85, v2
	v_lshl_or_b32 v190, v3, 2, s10
	v_mov_b32_e32 v191, s50
	s_mov_b32 s84, -4
	s_movk_i32 s85, 0x1c0
	s_movk_i32 s86, 0xe3f
	v_add_u32_e32 v144, v10, v13
	v_add_u32_e32 v212, v12, v16
	v_add_u32_e32 v213, v11, v15
	v_mov_b32_e32 v1, v0
	v_mov_b32_e32 v2, v0
	v_mov_b32_e32 v3, v0
	v_mov_b32_e32 v4, v0
	v_mov_b32_e32 v5, v0
	v_mov_b32_e32 v6, v0
	v_mov_b32_e32 v7, v0
	v_mov_b32_e32 v8, v0
	v_mov_b32_e32 v9, v0
	v_mov_b32_e32 v10, v0
	v_mov_b32_e32 v11, v0
	v_mov_b32_e32 v12, v0
	v_mov_b32_e32 v13, v0
	v_mov_b32_e32 v14, v0
	v_mov_b32_e32 v15, v0
	s_branch .LBB0_473

.LBB0_473:
	s_waitcnt vmcnt(22)
	ds_write_b128 v202, v[52:55] offset:17408
	ds_write_b128 v202, v[48:51] offset:17424
	s_waitcnt vmcnt(20)
	ds_write_b128 v203, v[60:63] offset:34816
	ds_write_b128 v203, v[56:59] offset:34832
	s_waitcnt vmcnt(19)
	ds_write_b128 v204, v[64:67] offset:53248
	s_waitcnt vmcnt(18)
	ds_write_b16 v144, v96 offset:62464
	ds_write_b16_d16_hi v144, v96 offset:62608
	ds_write_b16 v144, v97 offset:62752
	ds_write_b16_d16_hi v144, v97 offset:62896
	ds_write_b16 v144, v98 offset:63040
	ds_write_b16_d16_hi v144, v98 offset:63184
	ds_write_b16 v144, v99 offset:63328
	ds_write_b16_d16_hi v144, v99 offset:63472
	s_and_saveexec_b64 s[50:51], s[0:1]
	ds_write_b32 v205, v199
	s_or_b64 exec, exec, s[50:51]
	s_waitcnt lgkmcnt(0)
	s_barrier
	s_and_saveexec_b64 s[50:51], s[4:5]
	s_cbranch_execz .LBB0_477
	s_add_i32 s10, s85, 0xfffffe40
	s_add_i32 s87, s86, 0x1c0
	s_and_b64 s[52:53], s[48:49], exec
	s_cselect_b32 s10, s10, s87
	s_add_u32 s52, s46, s10
	s_addc_u32 s53, 0, s47
	s_lshl_b64 s[98:99], s[52:53], 11
	ds_read_b128 v[214:217], v209 offset:53248
	ds_read_b128 v[218:221], v210 offset:62464
	ds_read_b128 v[222:225], v209 offset:53280
	ds_read_b128 v[226:229], v210 offset:62496
	ds_read_b128 v[240:243], v209 offset:53312
	ds_read_b128 v[244:247], v210 offset:62528
	ds_read_b128 v[248:251], v209 offset:53344
	ds_read_b128 v[252:255], v210 offset:62560
	s_waitcnt lgkmcnt(6)
	v_mfma_f32_32x32x16_bf16 v[16:31], v[214:217], v[218:221], 0
	ds_read_b128 v[214:217], v206 offset:17408
	ds_read_b128 v[218:221], v207
	s_waitcnt lgkmcnt(6)
	v_mfma_f32_32x32x16_bf16 v[16:31], v[222:225], v[226:229], v[16:31]
	ds_read_b128 v[222:225], v206 offset:17440
	ds_read_b128 v[226:229], v207 offset:32
	s_waitcnt lgkmcnt(6)
	v_mfma_f32_32x32x16_bf16 v[16:31], v[240:243], v[244:247], v[16:31]
	ds_read_b128 v[240:243], v206 offset:17472
	ds_read_b128 v[244:247], v207 offset:64
	s_waitcnt lgkmcnt(6)
	v_mfma_f32_32x32x16_bf16 v[16:31], v[248:251], v[252:255], v[16:31]
	ds_read_b128 v[248:251], v206 offset:17504
	ds_read_b128 v[252:255], v207 offset:96
	s_waitcnt lgkmcnt(6)
	v_mfma_f32_32x32x16_bf16 v[32:47], v[214:217], v[218:221], 0
	ds_read_b128 v[214:217], v206 offset:17536
	ds_read_b128 v[218:221], v207 offset:128
	s_waitcnt lgkmcnt(6)
	v_mfma_f32_32x32x16_bf16 v[32:47], v[222:225], v[226:229], v[32:47]
	ds_read_b128 v[222:225], v206 offset:17568
	ds_read_b128 v[226:229], v207 offset:160
	s_waitcnt lgkmcnt(6)
	v_mfma_f32_32x32x16_bf16 v[32:47], v[240:243], v[244:247], v[32:47]
	ds_read_b128 v[240:243], v206 offset:17600
	ds_read_b128 v[244:247], v207 offset:192
	s_waitcnt lgkmcnt(6)
	v_mfma_f32_32x32x16_bf16 v[32:47], v[248:251], v[252:255], v[32:47]
	ds_read_b128 v[248:251], v206 offset:17632
	ds_read_b128 v[252:255], v207 offset:224
	s_waitcnt lgkmcnt(6)
	v_mfma_f32_32x32x16_bf16 v[32:47], v[214:217], v[218:221], v[32:47]
	s_waitcnt lgkmcnt(4)
	v_mfma_f32_32x32x16_bf16 v[32:47], v[222:225], v[226:229], v[32:47]
	s_waitcnt lgkmcnt(2)
	v_mfma_f32_32x32x16_bf16 v[32:47], v[240:243], v[244:247], v[32:47]
	s_waitcnt lgkmcnt(0)
	v_mfma_f32_32x32x16_bf16 v[32:47], v[248:251], v[252:255], v[32:47]
	s_nop 11
	v_add_f32_e32 v236, v16, v32
	v_cvt_pk_bf16_f32 v236, v236, s0
	v_lshl_add_u64 v[226:227], s[98:99], 0, v[152:153]
	global_store_short v[226:227], v236, off
	v_add_f32_e32 v237, v17, v33
	v_cvt_pk_bf16_f32 v237, v237, s0
	v_lshl_add_u64 v[228:229], s[98:99], 0, v[154:155]
	global_store_short v[228:229], v237, off
	v_add_f32_e32 v236, v18, v34
	v_cvt_pk_bf16_f32 v236, v236, s0
	v_lshl_add_u64 v[226:227], s[98:99], 0, v[156:157]
	global_store_short v[226:227], v236, off
	v_add_f32_e32 v237, v19, v35
	v_cvt_pk_bf16_f32 v237, v237, s0
	v_lshl_add_u64 v[228:229], s[98:99], 0, v[158:159]
	global_store_short v[228:229], v237, off
	v_add_f32_e32 v236, v20, v36
	v_cvt_pk_bf16_f32 v236, v236, s0
	v_lshl_add_u64 v[226:227], s[98:99], 0, v[160:161]
	global_store_short v[226:227], v236, off
	v_add_f32_e32 v237, v21, v37
	v_cvt_pk_bf16_f32 v237, v237, s0
	v_lshl_add_u64 v[228:229], s[98:99], 0, v[162:163]
	global_store_short v[228:229], v237, off
	v_add_f32_e32 v236, v22, v38
	v_cvt_pk_bf16_f32 v236, v236, s0
	v_lshl_add_u64 v[226:227], s[98:99], 0, v[164:165]
	global_store_short v[226:227], v236, off
	v_add_f32_e32 v237, v23, v39
	v_cvt_pk_bf16_f32 v237, v237, s0
	v_lshl_add_u64 v[228:229], s[98:99], 0, v[166:167]
	global_store_short v[228:229], v237, off
	v_add_f32_e32 v236, v24, v40
	v_cvt_pk_bf16_f32 v236, v236, s0
	v_lshl_add_u64 v[226:227], s[98:99], 0, v[168:169]
	global_store_short v[226:227], v236, off
	v_add_f32_e32 v237, v25, v41
	v_cvt_pk_bf16_f32 v237, v237, s0
	v_lshl_add_u64 v[228:229], s[98:99], 0, v[170:171]
	global_store_short v[228:229], v237, off
	v_add_f32_e32 v236, v26, v42
	v_cvt_pk_bf16_f32 v236, v236, s0
	v_lshl_add_u64 v[226:227], s[98:99], 0, v[172:173]
	global_store_short v[226:227], v236, off
	v_add_f32_e32 v237, v27, v43
	v_cvt_pk_bf16_f32 v237, v237, s0
	v_lshl_add_u64 v[228:229], s[98:99], 0, v[174:175]
	global_store_short v[228:229], v237, off
	v_add_f32_e32 v236, v28, v44
	v_cvt_pk_bf16_f32 v236, v236, s0
	v_lshl_add_u64 v[226:227], s[98:99], 0, v[176:177]
	global_store_short v[226:227], v236, off
	v_add_f32_e32 v237, v29, v45
	v_cvt_pk_bf16_f32 v237, v237, s0
	v_lshl_add_u64 v[228:229], s[98:99], 0, v[178:179]
	global_store_short v[228:229], v237, off
	v_add_f32_e32 v236, v30, v46
	v_cvt_pk_bf16_f32 v236, v236, s0
	v_lshl_add_u64 v[226:227], s[98:99], 0, v[180:181]
	global_store_short v[226:227], v236, off
	v_add_f32_e32 v237, v31, v47
	v_cvt_pk_bf16_f32 v237, v237, s0
	v_lshl_add_u64 v[228:229], s[98:99], 0, v[182:183]
	global_store_short v[228:229], v237, off

.Lsw0_join:
	ds_write_b16 v144, v120 offset:62464
	ds_write_b16_d16_hi v144, v120 offset:62608
	ds_write_b16 v144, v121 offset:62752
	ds_write_b16_d16_hi v144, v121 offset:62896
	ds_write_b16 v144, v122 offset:63040
	ds_write_b16_d16_hi v144, v122 offset:63184
	ds_write_b16 v144, v123 offset:63328
	ds_write_b16_d16_hi v144, v123 offset:63472
	s_and_saveexec_b64 s[52:53], s[0:1]
	ds_write_b32 v205, v198
	s_or_b64 exec, exec, s[52:53]
	s_waitcnt lgkmcnt(0)
	s_barrier
	s_and_saveexec_b64 s[52:53], s[4:5]
	s_cbranch_execz .LBB0_485
	s_add_i32 s10, s85, 0xfffffe80
	s_add_i32 s87, s86, 0x180
	s_and_b64 s[96:97], s[48:49], exec
	s_cselect_b32 s10, s10, s87
	s_add_u32 s96, s46, s10
	s_addc_u32 s97, 0, s47
	s_lshl_b64 s[98:99], s[96:97], 11
	ds_read_b128 v[214:217], v209 offset:53248
	ds_read_b128 v[218:221], v210 offset:62464
	ds_read_b128 v[222:225], v209 offset:53280
	ds_read_b128 v[226:229], v210 offset:62496
	ds_read_b128 v[240:243], v209 offset:53312
	ds_read_b128 v[244:247], v210 offset:62528
	ds_read_b128 v[248:251], v209 offset:53344
	ds_read_b128 v[252:255], v210 offset:62560
	s_waitcnt lgkmcnt(6)
	v_mfma_f32_32x32x16_bf16 v[16:31], v[214:217], v[218:221], 0
	ds_read_b128 v[214:217], v206 offset:17408
	ds_read_b128 v[218:221], v207
	s_waitcnt lgkmcnt(6)
	v_mfma_f32_32x32x16_bf16 v[16:31], v[222:225], v[226:229], v[16:31]
	ds_read_b128 v[222:225], v206 offset:17440
	ds_read_b128 v[226:229], v207 offset:32
	s_waitcnt lgkmcnt(6)
	v_mfma_f32_32x32x16_bf16 v[16:31], v[240:243], v[244:247], v[16:31]
	ds_read_b128 v[240:243], v206 offset:17472
	ds_read_b128 v[244:247], v207 offset:64
	s_waitcnt lgkmcnt(6)
	v_mfma_f32_32x32x16_bf16 v[16:31], v[248:251], v[252:255], v[16:31]
	ds_read_b128 v[248:251], v206 offset:17504
	ds_read_b128 v[252:255], v207 offset:96
	s_waitcnt lgkmcnt(6)
	v_mfma_f32_32x32x16_bf16 v[32:47], v[214:217], v[218:221], 0
	ds_read_b128 v[214:217], v206 offset:17536
	ds_read_b128 v[218:221], v207 offset:128
	s_waitcnt lgkmcnt(6)
	v_mfma_f32_32x32x16_bf16 v[32:47], v[222:225], v[226:229], v[32:47]
	ds_read_b128 v[222:225], v206 offset:17568
	ds_read_b128 v[226:229], v207 offset:160
	s_waitcnt lgkmcnt(6)
	v_mfma_f32_32x32x16_bf16 v[32:47], v[240:243], v[244:247], v[32:47]
	ds_read_b128 v[240:243], v206 offset:17600
	ds_read_b128 v[244:247], v207 offset:192
	s_waitcnt lgkmcnt(6)
	v_mfma_f32_32x32x16_bf16 v[32:47], v[248:251], v[252:255], v[32:47]
	ds_read_b128 v[248:251], v206 offset:17632
	ds_read_b128 v[252:255], v207 offset:224
	s_waitcnt lgkmcnt(6)
	v_mfma_f32_32x32x16_bf16 v[32:47], v[214:217], v[218:221], v[32:47]
	s_waitcnt lgkmcnt(4)
	v_mfma_f32_32x32x16_bf16 v[32:47], v[222:225], v[226:229], v[32:47]
	s_waitcnt lgkmcnt(2)
	v_mfma_f32_32x32x16_bf16 v[32:47], v[240:243], v[244:247], v[32:47]
	s_waitcnt lgkmcnt(0)
	v_mfma_f32_32x32x16_bf16 v[32:47], v[248:251], v[252:255], v[32:47]
	s_nop 11
	v_add_f32_e32 v236, v16, v32
	v_cvt_pk_bf16_f32 v236, v236, s0
	v_lshl_add_u64 v[226:227], s[98:99], 0, v[152:153]
	global_store_short v[226:227], v236, off
	v_add_f32_e32 v237, v17, v33
	v_cvt_pk_bf16_f32 v237, v237, s0
	v_lshl_add_u64 v[228:229], s[98:99], 0, v[154:155]
	global_store_short v[228:229], v237, off
	v_add_f32_e32 v236, v18, v34
	v_cvt_pk_bf16_f32 v236, v236, s0
	v_lshl_add_u64 v[226:227], s[98:99], 0, v[156:157]
	global_store_short v[226:227], v236, off
	v_add_f32_e32 v237, v19, v35
	v_cvt_pk_bf16_f32 v237, v237, s0
	v_lshl_add_u64 v[228:229], s[98:99], 0, v[158:159]
	global_store_short v[228:229], v237, off
	v_add_f32_e32 v236, v20, v36
	v_cvt_pk_bf16_f32 v236, v236, s0
	v_lshl_add_u64 v[226:227], s[98:99], 0, v[160:161]
	global_store_short v[226:227], v236, off
	v_add_f32_e32 v237, v21, v37
	v_cvt_pk_bf16_f32 v237, v237, s0
	v_lshl_add_u64 v[228:229], s[98:99], 0, v[162:163]
	global_store_short v[228:229], v237, off
	v_add_f32_e32 v236, v22, v38
	v_cvt_pk_bf16_f32 v236, v236, s0
	v_lshl_add_u64 v[226:227], s[98:99], 0, v[164:165]
	global_store_short v[226:227], v236, off
	v_add_f32_e32 v237, v23, v39
	v_cvt_pk_bf16_f32 v237, v237, s0
	v_lshl_add_u64 v[228:229], s[98:99], 0, v[166:167]
	global_store_short v[228:229], v237, off
	v_add_f32_e32 v236, v24, v40
	v_cvt_pk_bf16_f32 v236, v236, s0
	v_lshl_add_u64 v[226:227], s[98:99], 0, v[168:169]
	global_store_short v[226:227], v236, off
	v_add_f32_e32 v237, v25, v41
	v_cvt_pk_bf16_f32 v237, v237, s0
	v_lshl_add_u64 v[228:229], s[98:99], 0, v[170:171]
	global_store_short v[228:229], v237, off
	v_add_f32_e32 v236, v26, v42
	v_cvt_pk_bf16_f32 v236, v236, s0
	v_lshl_add_u64 v[226:227], s[98:99], 0, v[172:173]
	global_store_short v[226:227], v236, off
	v_add_f32_e32 v237, v27, v43
	v_cvt_pk_bf16_f32 v237, v237, s0
	v_lshl_add_u64 v[228:229], s[98:99], 0, v[174:175]
	global_store_short v[228:229], v237, off
	v_add_f32_e32 v236, v28, v44
	v_cvt_pk_bf16_f32 v236, v236, s0
	v_lshl_add_u64 v[226:227], s[98:99], 0, v[176:177]
	global_store_short v[226:227], v236, off
	v_add_f32_e32 v237, v29, v45
	v_cvt_pk_bf16_f32 v237, v237, s0
	v_lshl_add_u64 v[228:229], s[98:99], 0, v[178:179]
	global_store_short v[228:229], v237, off
	v_add_f32_e32 v236, v30, v46
	v_cvt_pk_bf16_f32 v236, v236, s0
	v_lshl_add_u64 v[226:227], s[98:99], 0, v[180:181]
	global_store_short v[226:227], v236, off
	v_add_f32_e32 v237, v31, v47
	v_cvt_pk_bf16_f32 v237, v237, s0
	v_lshl_add_u64 v[228:229], s[98:99], 0, v[182:183]
	global_store_short v[228:229], v237, off

.Lsw1_join:
	ds_write_b16 v144, v136 offset:62464
	ds_write_b16_d16_hi v144, v136 offset:62608
	ds_write_b16 v144, v137 offset:62752
	ds_write_b16_d16_hi v144, v137 offset:62896
	ds_write_b16 v144, v138 offset:63040
	ds_write_b16_d16_hi v144, v138 offset:63184
	ds_write_b16 v144, v139 offset:63328
	ds_write_b16_d16_hi v144, v139 offset:63472
	s_and_saveexec_b64 s[52:53], s[0:1]
	ds_write_b32 v205, v201
	s_or_b64 exec, exec, s[52:53]
	s_waitcnt lgkmcnt(0)
	s_barrier
	s_and_saveexec_b64 s[52:53], s[4:5]
	s_cbranch_execz .LBB0_493
	s_add_i32 s10, s85, 0xfffffec0
	s_add_i32 s87, s86, 0x140
	s_and_b64 s[96:97], s[48:49], exec
	s_cselect_b32 s10, s10, s87
	s_add_u32 s96, s46, s10
	s_addc_u32 s97, 0, s47
	s_lshl_b64 s[98:99], s[96:97], 11
	ds_read_b128 v[214:217], v209 offset:53248
	ds_read_b128 v[218:221], v210 offset:62464
	ds_read_b128 v[222:225], v209 offset:53280
	ds_read_b128 v[226:229], v210 offset:62496
	ds_read_b128 v[240:243], v209 offset:53312
	ds_read_b128 v[244:247], v210 offset:62528
	ds_read_b128 v[248:251], v209 offset:53344
	ds_read_b128 v[252:255], v210 offset:62560
	s_waitcnt lgkmcnt(6)
	v_mfma_f32_32x32x16_bf16 v[16:31], v[214:217], v[218:221], 0
	ds_read_b128 v[214:217], v206 offset:17408
	ds_read_b128 v[218:221], v207
	s_waitcnt lgkmcnt(6)
	v_mfma_f32_32x32x16_bf16 v[16:31], v[222:225], v[226:229], v[16:31]
	ds_read_b128 v[222:225], v206 offset:17440
	ds_read_b128 v[226:229], v207 offset:32
	s_waitcnt lgkmcnt(6)
	v_mfma_f32_32x32x16_bf16 v[16:31], v[240:243], v[244:247], v[16:31]
	ds_read_b128 v[240:243], v206 offset:17472
	ds_read_b128 v[244:247], v207 offset:64
	s_waitcnt lgkmcnt(6)
	v_mfma_f32_32x32x16_bf16 v[16:31], v[248:251], v[252:255], v[16:31]
	ds_read_b128 v[248:251], v206 offset:17504
	ds_read_b128 v[252:255], v207 offset:96
	s_waitcnt lgkmcnt(6)
	v_mfma_f32_32x32x16_bf16 v[32:47], v[214:217], v[218:221], 0
	ds_read_b128 v[214:217], v206 offset:17536
	ds_read_b128 v[218:221], v207 offset:128
	s_waitcnt lgkmcnt(6)
	v_mfma_f32_32x32x16_bf16 v[32:47], v[222:225], v[226:229], v[32:47]
	ds_read_b128 v[222:225], v206 offset:17568
	ds_read_b128 v[226:229], v207 offset:160
	s_waitcnt lgkmcnt(6)
	v_mfma_f32_32x32x16_bf16 v[32:47], v[240:243], v[244:247], v[32:47]
	ds_read_b128 v[240:243], v206 offset:17600
	ds_read_b128 v[244:247], v207 offset:192
	s_waitcnt lgkmcnt(6)
	v_mfma_f32_32x32x16_bf16 v[32:47], v[248:251], v[252:255], v[32:47]
	ds_read_b128 v[248:251], v206 offset:17632
	ds_read_b128 v[252:255], v207 offset:224
	s_waitcnt lgkmcnt(6)
	v_mfma_f32_32x32x16_bf16 v[32:47], v[214:217], v[218:221], v[32:47]
	s_waitcnt lgkmcnt(4)
	v_mfma_f32_32x32x16_bf16 v[32:47], v[222:225], v[226:229], v[32:47]
	s_waitcnt lgkmcnt(2)
	v_mfma_f32_32x32x16_bf16 v[32:47], v[240:243], v[244:247], v[32:47]
	s_waitcnt lgkmcnt(0)
	v_mfma_f32_32x32x16_bf16 v[32:47], v[248:251], v[252:255], v[32:47]
	s_nop 11
	v_add_f32_e32 v236, v16, v32
	v_cvt_pk_bf16_f32 v236, v236, s0
	v_lshl_add_u64 v[226:227], s[98:99], 0, v[152:153]
	global_store_short v[226:227], v236, off
	v_add_f32_e32 v237, v17, v33
	v_cvt_pk_bf16_f32 v237, v237, s0
	v_lshl_add_u64 v[228:229], s[98:99], 0, v[154:155]
	global_store_short v[228:229], v237, off
	v_add_f32_e32 v236, v18, v34
	v_cvt_pk_bf16_f32 v236, v236, s0
	v_lshl_add_u64 v[226:227], s[98:99], 0, v[156:157]
	global_store_short v[226:227], v236, off
	v_add_f32_e32 v237, v19, v35
	v_cvt_pk_bf16_f32 v237, v237, s0
	v_lshl_add_u64 v[228:229], s[98:99], 0, v[158:159]
	global_store_short v[228:229], v237, off
	v_add_f32_e32 v236, v20, v36
	v_cvt_pk_bf16_f32 v236, v236, s0
	v_lshl_add_u64 v[226:227], s[98:99], 0, v[160:161]
	global_store_short v[226:227], v236, off
	v_add_f32_e32 v237, v21, v37
	v_cvt_pk_bf16_f32 v237, v237, s0
	v_lshl_add_u64 v[228:229], s[98:99], 0, v[162:163]
	global_store_short v[228:229], v237, off
	v_add_f32_e32 v236, v22, v38
	v_cvt_pk_bf16_f32 v236, v236, s0
	v_lshl_add_u64 v[226:227], s[98:99], 0, v[164:165]
	global_store_short v[226:227], v236, off
	v_add_f32_e32 v237, v23, v39
	v_cvt_pk_bf16_f32 v237, v237, s0
	v_lshl_add_u64 v[228:229], s[98:99], 0, v[166:167]
	global_store_short v[228:229], v237, off
	v_add_f32_e32 v236, v24, v40
	v_cvt_pk_bf16_f32 v236, v236, s0
	v_lshl_add_u64 v[226:227], s[98:99], 0, v[168:169]
	global_store_short v[226:227], v236, off
	v_add_f32_e32 v237, v25, v41
	v_cvt_pk_bf16_f32 v237, v237, s0
	v_lshl_add_u64 v[228:229], s[98:99], 0, v[170:171]
	global_store_short v[228:229], v237, off
	v_add_f32_e32 v236, v26, v42
	v_cvt_pk_bf16_f32 v236, v236, s0
	v_lshl_add_u64 v[226:227], s[98:99], 0, v[172:173]
	global_store_short v[226:227], v236, off
	v_add_f32_e32 v237, v27, v43
	v_cvt_pk_bf16_f32 v237, v237, s0
	v_lshl_add_u64 v[228:229], s[98:99], 0, v[174:175]
	global_store_short v[228:229], v237, off
	v_add_f32_e32 v236, v28, v44
	v_cvt_pk_bf16_f32 v236, v236, s0
	v_lshl_add_u64 v[226:227], s[98:99], 0, v[176:177]
	global_store_short v[226:227], v236, off
	v_add_f32_e32 v237, v29, v45
	v_cvt_pk_bf16_f32 v237, v237, s0
	v_lshl_add_u64 v[228:229], s[98:99], 0, v[178:179]
	global_store_short v[228:229], v237, off
	v_add_f32_e32 v236, v30, v46
	v_cvt_pk_bf16_f32 v236, v236, s0
	v_lshl_add_u64 v[226:227], s[98:99], 0, v[180:181]
	global_store_short v[226:227], v236, off
	v_add_f32_e32 v237, v31, v47
	v_cvt_pk_bf16_f32 v237, v237, s0
	v_lshl_add_u64 v[228:229], s[98:99], 0, v[182:183]
	global_store_short v[228:229], v237, off

.Lsw2_join:
	ds_write_b16 v144, v140 offset:62464
	ds_write_b16_d16_hi v144, v140 offset:62608
	ds_write_b16 v144, v141 offset:62752
	ds_write_b16_d16_hi v144, v141 offset:62896
	ds_write_b16 v144, v142 offset:63040
	ds_write_b16_d16_hi v144, v142 offset:63184
	ds_write_b16 v144, v143 offset:63328
	ds_write_b16_d16_hi v144, v143 offset:63472
	s_and_saveexec_b64 s[52:53], s[0:1]
	ds_write_b32 v205, v200
	s_or_b64 exec, exec, s[52:53]
	s_waitcnt lgkmcnt(0)
	s_barrier
	s_and_saveexec_b64 s[52:53], s[4:5]
	s_cbranch_execz .LBB0_501
	s_add_i32 s10, s85, 0xffffff00
	s_add_i32 s87, s86, 0x100
	s_and_b64 s[96:97], s[48:49], exec
	s_cselect_b32 s10, s10, s87
	s_add_u32 s96, s46, s10
	s_addc_u32 s97, 0, s47
	s_lshl_b64 s[98:99], s[96:97], 11
	ds_read_b128 v[214:217], v209 offset:53248
	ds_read_b128 v[218:221], v210 offset:62464
	ds_read_b128 v[222:225], v209 offset:53280
	ds_read_b128 v[226:229], v210 offset:62496
	ds_read_b128 v[240:243], v209 offset:53312
	ds_read_b128 v[244:247], v210 offset:62528
	ds_read_b128 v[248:251], v209 offset:53344
	ds_read_b128 v[252:255], v210 offset:62560
	s_waitcnt lgkmcnt(6)
	v_mfma_f32_32x32x16_bf16 v[16:31], v[214:217], v[218:221], 0
	ds_read_b128 v[214:217], v206 offset:17408
	ds_read_b128 v[218:221], v207
	s_waitcnt lgkmcnt(6)
	v_mfma_f32_32x32x16_bf16 v[16:31], v[222:225], v[226:229], v[16:31]
	ds_read_b128 v[222:225], v206 offset:17440
	ds_read_b128 v[226:229], v207 offset:32
	s_waitcnt lgkmcnt(6)
	v_mfma_f32_32x32x16_bf16 v[16:31], v[240:243], v[244:247], v[16:31]
	ds_read_b128 v[240:243], v206 offset:17472
	ds_read_b128 v[244:247], v207 offset:64
	s_waitcnt lgkmcnt(6)
	v_mfma_f32_32x32x16_bf16 v[16:31], v[248:251], v[252:255], v[16:31]
	ds_read_b128 v[248:251], v206 offset:17504
	ds_read_b128 v[252:255], v207 offset:96
	s_waitcnt lgkmcnt(6)
	v_mfma_f32_32x32x16_bf16 v[32:47], v[214:217], v[218:221], 0
	ds_read_b128 v[214:217], v206 offset:17536
	ds_read_b128 v[218:221], v207 offset:128
	s_waitcnt lgkmcnt(6)
	v_mfma_f32_32x32x16_bf16 v[32:47], v[222:225], v[226:229], v[32:47]
	ds_read_b128 v[222:225], v206 offset:17568
	ds_read_b128 v[226:229], v207 offset:160
	s_waitcnt lgkmcnt(6)
	v_mfma_f32_32x32x16_bf16 v[32:47], v[240:243], v[244:247], v[32:47]
	ds_read_b128 v[240:243], v206 offset:17600
	ds_read_b128 v[244:247], v207 offset:192
	s_waitcnt lgkmcnt(6)
	v_mfma_f32_32x32x16_bf16 v[32:47], v[248:251], v[252:255], v[32:47]
	ds_read_b128 v[248:251], v206 offset:17632
	ds_read_b128 v[252:255], v207 offset:224
	s_waitcnt lgkmcnt(6)
	v_mfma_f32_32x32x16_bf16 v[32:47], v[214:217], v[218:221], v[32:47]
	s_waitcnt lgkmcnt(4)
	v_mfma_f32_32x32x16_bf16 v[32:47], v[222:225], v[226:229], v[32:47]
	s_waitcnt lgkmcnt(2)
	v_mfma_f32_32x32x16_bf16 v[32:47], v[240:243], v[244:247], v[32:47]
	s_waitcnt lgkmcnt(0)
	v_mfma_f32_32x32x16_bf16 v[32:47], v[248:251], v[252:255], v[32:47]
	s_nop 11
	v_add_f32_e32 v236, v16, v32
	v_cvt_pk_bf16_f32 v236, v236, s0
	v_lshl_add_u64 v[226:227], s[98:99], 0, v[152:153]
	global_store_short v[226:227], v236, off
	v_add_f32_e32 v237, v17, v33
	v_cvt_pk_bf16_f32 v237, v237, s0
	v_lshl_add_u64 v[228:229], s[98:99], 0, v[154:155]
	global_store_short v[228:229], v237, off
	v_add_f32_e32 v236, v18, v34
	v_cvt_pk_bf16_f32 v236, v236, s0
	v_lshl_add_u64 v[226:227], s[98:99], 0, v[156:157]
	global_store_short v[226:227], v236, off
	v_add_f32_e32 v237, v19, v35
	v_cvt_pk_bf16_f32 v237, v237, s0
	v_lshl_add_u64 v[228:229], s[98:99], 0, v[158:159]
	global_store_short v[228:229], v237, off
	v_add_f32_e32 v236, v20, v36
	v_cvt_pk_bf16_f32 v236, v236, s0
	v_lshl_add_u64 v[226:227], s[98:99], 0, v[160:161]
	global_store_short v[226:227], v236, off
	v_add_f32_e32 v237, v21, v37
	v_cvt_pk_bf16_f32 v237, v237, s0
	v_lshl_add_u64 v[228:229], s[98:99], 0, v[162:163]
	global_store_short v[228:229], v237, off
	v_add_f32_e32 v236, v22, v38
	v_cvt_pk_bf16_f32 v236, v236, s0
	v_lshl_add_u64 v[226:227], s[98:99], 0, v[164:165]
	global_store_short v[226:227], v236, off
	v_add_f32_e32 v237, v23, v39
	v_cvt_pk_bf16_f32 v237, v237, s0
	v_lshl_add_u64 v[228:229], s[98:99], 0, v[166:167]
	global_store_short v[228:229], v237, off
	v_add_f32_e32 v236, v24, v40
	v_cvt_pk_bf16_f32 v236, v236, s0
	v_lshl_add_u64 v[226:227], s[98:99], 0, v[168:169]
	global_store_short v[226:227], v236, off
	v_add_f32_e32 v237, v25, v41
	v_cvt_pk_bf16_f32 v237, v237, s0
	v_lshl_add_u64 v[228:229], s[98:99], 0, v[170:171]
	global_store_short v[228:229], v237, off
	v_add_f32_e32 v236, v26, v42
	v_cvt_pk_bf16_f32 v236, v236, s0
	v_lshl_add_u64 v[226:227], s[98:99], 0, v[172:173]
	global_store_short v[226:227], v236, off
	v_add_f32_e32 v237, v27, v43
	v_cvt_pk_bf16_f32 v237, v237, s0
	v_lshl_add_u64 v[228:229], s[98:99], 0, v[174:175]
	global_store_short v[228:229], v237, off
	v_add_f32_e32 v236, v28, v44
	v_cvt_pk_bf16_f32 v236, v236, s0
	v_lshl_add_u64 v[226:227], s[98:99], 0, v[176:177]
	global_store_short v[226:227], v236, off
	v_add_f32_e32 v237, v29, v45
	v_cvt_pk_bf16_f32 v237, v237, s0
	v_lshl_add_u64 v[228:229], s[98:99], 0, v[178:179]
	global_store_short v[228:229], v237, off
	v_add_f32_e32 v236, v30, v46
	v_cvt_pk_bf16_f32 v236, v236, s0
	v_lshl_add_u64 v[226:227], s[98:99], 0, v[180:181]
	global_store_short v[226:227], v236, off
	v_add_f32_e32 v237, v31, v47
	v_cvt_pk_bf16_f32 v237, v237, s0
	v_lshl_add_u64 v[228:229], s[98:99], 0, v[182:183]
	global_store_short v[228:229], v237, off

.LBB0_863:
	s_or_b64 exec, exec, s[4:5]
	s_lshr_b32 s80, s77, 2
	s_lshr_b32 s81, s77, 3
	s_and_b64 s[4:5], s[48:49], exec
	s_cselect_b32 s78, s68, 0x36c00000
	s_cselect_b32 s4, 0xc0, s67
	s_add_u32 s78, s94, s78
	s_addc_u32 s79, s95, 0
	s_lshl_b32 s10, s10, 1
	s_add_u32 s10, s78, s10
	s_addc_u32 s79, s79, 0
	s_mov_b32 s5, s11
	s_add_u32 s78, s10, s53
	s_addc_u32 s79, s79, 0
	s_or_b64 s[4:5], s[4:5], s[46:47]
	v_lshl_add_u64 v[10:11], s[4:5], 0, v[10:11]
	v_lshlrev_b64 v[10:11], 11, v[10:11]
	v_lshl_add_u64 v[10:11], v[146:147], 0, v[10:11]
	global_load_dwordx4 v[140:143], v[10:11], off
	v_lshlrev_b32_e32 v12, 5, v9
	v_and_b32_e32 v19, 32, v12
	v_and_b32_e32 v17, 31, v20
	v_lshlrev_b32_e32 v12, 1, v19
	v_mov_b32_e32 v13, v145
	v_lshl_add_u64 v[12:13], s[78:79], 0, v[12:13]
	v_lshlrev_b32_e32 v14, 1, v17
	v_mov_b32_e32 v15, v145
	v_lshl_add_u64 v[150:151], v[12:13], 0, v[14:15]
	v_mul_lo_u32 v12, v0, s69
	v_mul_lo_u32 v13, v21, s74
	v_ashrrev_i32_e32 v18, 7, v20
	v_add_u32_e32 v12, 0, v12
	v_add3_u32 v203, 0, v13, v8
	v_lshlrev_b32_e32 v8, 7, v0
	v_lshlrev_b32_e32 v16, 3, v23
	v_sub_u32_e32 v8, v12, v8
	v_lshlrev_b32_e32 v11, 5, v18
	v_lshl_add_u32 v202, v144, 1, v12
	v_lshl_add_u32 v204, v16, 1, v8
	v_lshrrev_b32_e32 v8, 5, v22
	v_and_b32_e32 v12, 32, v11
	v_lshlrev_b32_e32 v15, 3, v8
	v_lshlrev_b32_e32 v16, 4, v8
	v_lshl_or_b32 v8, v8, 2, v12
	v_mad_i32_i24 v154, v8, s52, s52
	v_add_u32_e32 v156, s52, v154
	v_add_u32_e32 v158, s52, v156
	v_mad_i32_i24 v160, s52, 5, v158
	v_add_u32_e32 v162, s52, v160
	v_add_u32_e32 v164, s52, v162
	v_add_u32_e32 v166, s52, v164
	v_mad_i32_i24 v168, s52, 5, v166
	s_and_b32 s10, s80, 1
	s_and_b32 s78, s81, 3
	v_add_u32_e32 v170, s52, v168
	s_lshl_b32 s53, s10, 5
	s_lshl_b32 s10, s10, 15
	s_lshl_b32 s79, s78, 8
	v_add_u32_e32 v172, s52, v170
	v_or_b32_e32 v13, v12, v17
	v_add_u32_e32 v174, s52, v172
	s_add_u32 s50, s53, s50
	v_mul_u32_u24_e32 v14, 0x110, v13
	v_mad_i32_i24 v176, s52, 5, v174
	s_addc_u32 s51, 0, s51
	v_add3_u32 v206, 0, v14, v16
	v_or_b32_e32 v14, v19, v17
	v_add_u32_e32 v178, s52, v176
	s_add_u32 s50, s50, s78
	v_mad_u32_u24 v19, v14, s69, 0
	v_lshlrev_b32_e32 v13, 7, v13
	v_add_u32_e32 v180, s52, v178
	s_addc_u32 s51, s51, 0
	v_add_u32_e32 v207, v19, v16
	v_sub_u32_e32 v209, v206, v13
	v_lshlrev_b32_e32 v13, 7, v14
	v_mul_i32_i24_e32 v152, s52, v8
	v_add_u32_e32 v182, s52, v180
	s_lshl_b64 s[52:53], s[50:51], 19
	v_cmp_gt_i32_e64 s[4:5], 4, v9
	v_sub_u32_e32 v210, v207, v13
	v_mul_lo_u32 v13, v9, s76
	v_mov_b32_e32 v9, s53
	v_or_b32_e32 v8, s52, v144
	v_lshl_add_u64 v[184:185], v[6:7], 1, v[8:9]
	s_lshl_b64 s[52:53], s[50:51], 20
	v_and_b32_e32 v6, 3, v20
	v_lshl_or_b32 v6, v6, 5, s52
	s_add_u32 s52, s10, s46
	v_or_b32_e32 v11, v11, v17
	v_mov_b32_e32 v7, s53
	s_addc_u32 s53, 0, s47
	s_lshl_b64 s[50:51], s[50:51], 15
	s_waitcnt lgkmcnt(0)
	s_barrier
	v_and_b32_e32 v12, 0xffffff80, v20
	v_mul_lo_u32 v11, v11, s74
	v_lshl_add_u64 v[0:1], s[52:53], 0, v[0:1]
	s_add_u32 s10, s50, 0x3ec00c00
	v_lshl_add_u32 v10, v22, 1, 0
	v_add_u32_e32 v12, s75, v12
	v_add3_u32 v211, 0, v11, v16
	v_lshl_add_u32 v11, v18, 6, v19
	v_lshlrev_b64 v[188:189], 10, v[0:1]
	s_addc_u32 s50, s51, 0
	v_mov_b32_e32 v0, 0
	v_lshl_add_u32 v205, v20, 2, s75
	v_ashrrev_i32_e32 v153, 31, v152
	v_ashrrev_i32_e32 v155, 31, v154
	v_ashrrev_i32_e32 v157, 31, v156
	v_ashrrev_i32_e32 v159, 31, v158
	v_ashrrev_i32_e32 v161, 31, v160
	v_ashrrev_i32_e32 v163, 31, v162
	v_ashrrev_i32_e32 v165, 31, v164
	v_ashrrev_i32_e32 v167, 31, v166
	v_ashrrev_i32_e32 v169, 31, v168
	v_ashrrev_i32_e32 v171, 31, v170
	v_ashrrev_i32_e32 v173, 31, v172
	v_ashrrev_i32_e32 v175, 31, v174
	v_ashrrev_i32_e32 v177, 31, v176
	v_ashrrev_i32_e32 v179, 31, v178
	v_ashrrev_i32_e32 v181, 31, v180
	v_ashrrev_i32_e32 v183, 31, v182
	v_lshlrev_b64 v[152:153], 11, v[152:153]
	v_lshl_add_u64 v[152:153], v[150:151], 0, v[152:153]
	v_lshlrev_b64 v[154:155], 11, v[154:155]
	v_lshl_add_u64 v[154:155], v[150:151], 0, v[154:155]
	v_lshlrev_b64 v[156:157], 11, v[156:157]
	v_lshl_add_u64 v[156:157], v[150:151], 0, v[156:157]
	v_lshlrev_b64 v[158:159], 11, v[158:159]
	v_lshl_add_u64 v[158:159], v[150:151], 0, v[158:159]
	v_lshlrev_b64 v[160:161], 11, v[160:161]
	v_lshl_add_u64 v[160:161], v[150:151], 0, v[160:161]
	v_lshlrev_b64 v[162:163], 11, v[162:163]
	v_lshl_add_u64 v[162:163], v[150:151], 0, v[162:163]
	v_lshlrev_b64 v[164:165], 11, v[164:165]
	v_lshl_add_u64 v[164:165], v[150:151], 0, v[164:165]
	v_lshlrev_b64 v[166:167], 11, v[166:167]
	v_lshl_add_u64 v[166:167], v[150:151], 0, v[166:167]
	v_lshlrev_b64 v[168:169], 11, v[168:169]
	v_lshl_add_u64 v[168:169], v[150:151], 0, v[168:169]
	v_lshlrev_b64 v[170:171], 11, v[170:171]
	v_lshl_add_u64 v[170:171], v[150:151], 0, v[170:171]
	v_lshlrev_b64 v[172:173], 11, v[172:173]
	v_lshl_add_u64 v[172:173], v[150:151], 0, v[172:173]
	v_lshlrev_b64 v[174:175], 11, v[174:175]
	v_lshl_add_u64 v[174:175], v[150:151], 0, v[174:175]
	v_lshlrev_b64 v[176:177], 11, v[176:177]
	v_lshl_add_u64 v[176:177], v[150:151], 0, v[176:177]
	v_lshlrev_b64 v[178:179], 11, v[178:179]
	v_lshl_add_u64 v[178:179], v[150:151], 0, v[178:179]
	v_lshlrev_b64 v[180:181], 11, v[180:181]
	v_lshl_add_u64 v[180:181], v[150:151], 0, v[180:181]
	v_lshlrev_b64 v[182:183], 11, v[182:183]
	v_lshl_add_u64 v[182:183], v[150:151], 0, v[182:183]
	v_lshl_add_u64 v[186:187], v[4:5], 1, v[6:7]
	v_or3_b32 v188, v188, s79, v2
	v_lshl_or_b32 v190, v3, 2, s10
	v_mov_b32_e32 v191, s50
	s_mov_b32 s78, -4
	s_movk_i32 s79, 0x1c0
	s_movk_i32 s80, 0xe3f
	v_add_u32_e32 v144, v10, v13
	v_add_u32_e32 v212, v12, v16
	v_add_u32_e32 v213, v11, v15
	v_mov_b32_e32 v1, v0
	v_mov_b32_e32 v2, v0
	v_mov_b32_e32 v3, v0
	v_mov_b32_e32 v4, v0
	v_mov_b32_e32 v5, v0
	v_mov_b32_e32 v6, v0
	v_mov_b32_e32 v7, v0
	v_mov_b32_e32 v8, v0
	v_mov_b32_e32 v9, v0
	v_mov_b32_e32 v10, v0
	v_mov_b32_e32 v11, v0
	v_mov_b32_e32 v12, v0
	v_mov_b32_e32 v13, v0
	v_mov_b32_e32 v14, v0
	v_mov_b32_e32 v15, v0
	s_branch .LBB0_866

.LBB0_866:
	s_waitcnt vmcnt(22)
	ds_write_b128 v202, v[52:55] offset:17408
	ds_write_b128 v202, v[48:51] offset:17424
	s_waitcnt vmcnt(20)
	ds_write_b128 v203, v[60:63] offset:34816
	ds_write_b128 v203, v[56:59] offset:34832
	s_waitcnt vmcnt(19)
	ds_write_b128 v204, v[64:67] offset:53248
	s_waitcnt vmcnt(18)
	ds_write_b16 v144, v96 offset:62464
	ds_write_b16_d16_hi v144, v96 offset:62608
	ds_write_b16 v144, v97 offset:62752
	ds_write_b16_d16_hi v144, v97 offset:62896
	ds_write_b16 v144, v98 offset:63040
	ds_write_b16_d16_hi v144, v98 offset:63184
	ds_write_b16 v144, v99 offset:63328
	ds_write_b16_d16_hi v144, v99 offset:63472
	s_and_saveexec_b64 s[50:51], s[0:1]
	ds_write_b32 v205, v199
	s_or_b64 exec, exec, s[50:51]
	s_waitcnt lgkmcnt(0)
	s_barrier
	s_and_saveexec_b64 s[50:51], s[4:5]
	s_cbranch_execz .LBB0_870
	s_add_i32 s10, s79, 0xfffffe40
	s_add_i32 s81, s80, 0x1c0
	s_and_b64 s[52:53], s[48:49], exec
	s_cselect_b32 s10, s10, s81
	s_add_u32 s52, s46, s10
	s_addc_u32 s53, 0, s47
	s_lshl_b64 s[98:99], s[52:53], 11
	ds_read_b128 v[214:217], v209 offset:53248
	ds_read_b128 v[218:221], v210 offset:62464
	ds_read_b128 v[222:225], v209 offset:53280
	ds_read_b128 v[226:229], v210 offset:62496
	ds_read_b128 v[240:243], v209 offset:53312
	ds_read_b128 v[244:247], v210 offset:62528
	ds_read_b128 v[248:251], v209 offset:53344
	ds_read_b128 v[252:255], v210 offset:62560
	s_waitcnt lgkmcnt(6)
	v_mfma_f32_32x32x16_bf16 v[16:31], v[214:217], v[218:221], 0
	ds_read_b128 v[214:217], v206 offset:17408
	ds_read_b128 v[218:221], v207
	s_waitcnt lgkmcnt(6)
	v_mfma_f32_32x32x16_bf16 v[16:31], v[222:225], v[226:229], v[16:31]
	ds_read_b128 v[222:225], v206 offset:17440
	ds_read_b128 v[226:229], v207 offset:32
	s_waitcnt lgkmcnt(6)
	v_mfma_f32_32x32x16_bf16 v[16:31], v[240:243], v[244:247], v[16:31]
	ds_read_b128 v[240:243], v206 offset:17472
	ds_read_b128 v[244:247], v207 offset:64
	s_waitcnt lgkmcnt(6)
	v_mfma_f32_32x32x16_bf16 v[16:31], v[248:251], v[252:255], v[16:31]
	ds_read_b128 v[248:251], v206 offset:17504
	ds_read_b128 v[252:255], v207 offset:96
	s_waitcnt lgkmcnt(6)
	v_mfma_f32_32x32x16_bf16 v[32:47], v[214:217], v[218:221], 0
	ds_read_b128 v[214:217], v206 offset:17536
	ds_read_b128 v[218:221], v207 offset:128
	s_waitcnt lgkmcnt(6)
	v_mfma_f32_32x32x16_bf16 v[32:47], v[222:225], v[226:229], v[32:47]
	ds_read_b128 v[222:225], v206 offset:17568
	ds_read_b128 v[226:229], v207 offset:160
	s_waitcnt lgkmcnt(6)
	v_mfma_f32_32x32x16_bf16 v[32:47], v[240:243], v[244:247], v[32:47]
	ds_read_b128 v[240:243], v206 offset:17600
	ds_read_b128 v[244:247], v207 offset:192
	s_waitcnt lgkmcnt(6)
	v_mfma_f32_32x32x16_bf16 v[32:47], v[248:251], v[252:255], v[32:47]
	ds_read_b128 v[248:251], v206 offset:17632
	ds_read_b128 v[252:255], v207 offset:224
	s_waitcnt lgkmcnt(6)
	v_mfma_f32_32x32x16_bf16 v[32:47], v[214:217], v[218:221], v[32:47]
	s_waitcnt lgkmcnt(4)
	v_mfma_f32_32x32x16_bf16 v[32:47], v[222:225], v[226:229], v[32:47]
	s_waitcnt lgkmcnt(2)
	v_mfma_f32_32x32x16_bf16 v[32:47], v[240:243], v[244:247], v[32:47]
	s_waitcnt lgkmcnt(0)
	v_mfma_f32_32x32x16_bf16 v[32:47], v[248:251], v[252:255], v[32:47]
	s_nop 11
	v_add_f32_e32 v236, v16, v32
	v_cvt_pk_bf16_f32 v236, v236, s0
	v_lshl_add_u64 v[226:227], s[98:99], 0, v[152:153]
	global_store_short v[226:227], v236, off
	v_add_f32_e32 v237, v17, v33
	v_cvt_pk_bf16_f32 v237, v237, s0
	v_lshl_add_u64 v[228:229], s[98:99], 0, v[154:155]
	global_store_short v[228:229], v237, off
	v_add_f32_e32 v236, v18, v34
	v_cvt_pk_bf16_f32 v236, v236, s0
	v_lshl_add_u64 v[226:227], s[98:99], 0, v[156:157]
	global_store_short v[226:227], v236, off
	v_add_f32_e32 v237, v19, v35
	v_cvt_pk_bf16_f32 v237, v237, s0
	v_lshl_add_u64 v[228:229], s[98:99], 0, v[158:159]
	global_store_short v[228:229], v237, off
	v_add_f32_e32 v236, v20, v36
	v_cvt_pk_bf16_f32 v236, v236, s0
	v_lshl_add_u64 v[226:227], s[98:99], 0, v[160:161]
	global_store_short v[226:227], v236, off
	v_add_f32_e32 v237, v21, v37
	v_cvt_pk_bf16_f32 v237, v237, s0
	v_lshl_add_u64 v[228:229], s[98:99], 0, v[162:163]
	global_store_short v[228:229], v237, off
	v_add_f32_e32 v236, v22, v38
	v_cvt_pk_bf16_f32 v236, v236, s0
	v_lshl_add_u64 v[226:227], s[98:99], 0, v[164:165]
	global_store_short v[226:227], v236, off
	v_add_f32_e32 v237, v23, v39
	v_cvt_pk_bf16_f32 v237, v237, s0
	v_lshl_add_u64 v[228:229], s[98:99], 0, v[166:167]
	global_store_short v[228:229], v237, off
	v_add_f32_e32 v236, v24, v40
	v_cvt_pk_bf16_f32 v236, v236, s0
	v_lshl_add_u64 v[226:227], s[98:99], 0, v[168:169]
	global_store_short v[226:227], v236, off
	v_add_f32_e32 v237, v25, v41
	v_cvt_pk_bf16_f32 v237, v237, s0
	v_lshl_add_u64 v[228:229], s[98:99], 0, v[170:171]
	global_store_short v[228:229], v237, off
	v_add_f32_e32 v236, v26, v42
	v_cvt_pk_bf16_f32 v236, v236, s0
	v_lshl_add_u64 v[226:227], s[98:99], 0, v[172:173]
	global_store_short v[226:227], v236, off
	v_add_f32_e32 v237, v27, v43
	v_cvt_pk_bf16_f32 v237, v237, s0
	v_lshl_add_u64 v[228:229], s[98:99], 0, v[174:175]
	global_store_short v[228:229], v237, off
	v_add_f32_e32 v236, v28, v44
	v_cvt_pk_bf16_f32 v236, v236, s0
	v_lshl_add_u64 v[226:227], s[98:99], 0, v[176:177]
	global_store_short v[226:227], v236, off
	v_add_f32_e32 v237, v29, v45
	v_cvt_pk_bf16_f32 v237, v237, s0
	v_lshl_add_u64 v[228:229], s[98:99], 0, v[178:179]
	global_store_short v[228:229], v237, off
	v_add_f32_e32 v236, v30, v46
	v_cvt_pk_bf16_f32 v236, v236, s0
	v_lshl_add_u64 v[226:227], s[98:99], 0, v[180:181]
	global_store_short v[226:227], v236, off
	v_add_f32_e32 v237, v31, v47
	v_cvt_pk_bf16_f32 v237, v237, s0
	v_lshl_add_u64 v[228:229], s[98:99], 0, v[182:183]
	global_store_short v[228:229], v237, off

.Lsw3_join:
	ds_write_b16 v144, v120 offset:62464
	ds_write_b16_d16_hi v144, v120 offset:62608
	ds_write_b16 v144, v121 offset:62752
	ds_write_b16_d16_hi v144, v121 offset:62896
	ds_write_b16 v144, v122 offset:63040
	ds_write_b16_d16_hi v144, v122 offset:63184
	ds_write_b16 v144, v123 offset:63328
	ds_write_b16_d16_hi v144, v123 offset:63472
	s_and_saveexec_b64 s[52:53], s[0:1]
	ds_write_b32 v205, v198
	s_or_b64 exec, exec, s[52:53]
	s_waitcnt lgkmcnt(0)
	s_barrier
	s_and_saveexec_b64 s[52:53], s[4:5]
	s_cbranch_execz .LBB0_878
	s_add_i32 s10, s79, 0xfffffe80
	s_add_i32 s81, s80, 0x180
	s_and_b64 s[84:85], s[48:49], exec
	s_cselect_b32 s10, s10, s81
	s_add_u32 s84, s46, s10
	s_addc_u32 s85, 0, s47
	s_lshl_b64 s[98:99], s[84:85], 11
	ds_read_b128 v[214:217], v209 offset:53248
	ds_read_b128 v[218:221], v210 offset:62464
	ds_read_b128 v[222:225], v209 offset:53280
	ds_read_b128 v[226:229], v210 offset:62496
	ds_read_b128 v[240:243], v209 offset:53312
	ds_read_b128 v[244:247], v210 offset:62528
	ds_read_b128 v[248:251], v209 offset:53344
	ds_read_b128 v[252:255], v210 offset:62560
	s_waitcnt lgkmcnt(6)
	v_mfma_f32_32x32x16_bf16 v[16:31], v[214:217], v[218:221], 0
	ds_read_b128 v[214:217], v206 offset:17408
	ds_read_b128 v[218:221], v207
	s_waitcnt lgkmcnt(6)
	v_mfma_f32_32x32x16_bf16 v[16:31], v[222:225], v[226:229], v[16:31]
	ds_read_b128 v[222:225], v206 offset:17440
	ds_read_b128 v[226:229], v207 offset:32
	s_waitcnt lgkmcnt(6)
	v_mfma_f32_32x32x16_bf16 v[16:31], v[240:243], v[244:247], v[16:31]
	ds_read_b128 v[240:243], v206 offset:17472
	ds_read_b128 v[244:247], v207 offset:64
	s_waitcnt lgkmcnt(6)
	v_mfma_f32_32x32x16_bf16 v[16:31], v[248:251], v[252:255], v[16:31]
	ds_read_b128 v[248:251], v206 offset:17504
	ds_read_b128 v[252:255], v207 offset:96
	s_waitcnt lgkmcnt(6)
	v_mfma_f32_32x32x16_bf16 v[32:47], v[214:217], v[218:221], 0
	ds_read_b128 v[214:217], v206 offset:17536
	ds_read_b128 v[218:221], v207 offset:128
	s_waitcnt lgkmcnt(6)
	v_mfma_f32_32x32x16_bf16 v[32:47], v[222:225], v[226:229], v[32:47]
	ds_read_b128 v[222:225], v206 offset:17568
	ds_read_b128 v[226:229], v207 offset:160
	s_waitcnt lgkmcnt(6)
	v_mfma_f32_32x32x16_bf16 v[32:47], v[240:243], v[244:247], v[32:47]
	ds_read_b128 v[240:243], v206 offset:17600
	ds_read_b128 v[244:247], v207 offset:192
	s_waitcnt lgkmcnt(6)
	v_mfma_f32_32x32x16_bf16 v[32:47], v[248:251], v[252:255], v[32:47]
	ds_read_b128 v[248:251], v206 offset:17632
	ds_read_b128 v[252:255], v207 offset:224
	s_waitcnt lgkmcnt(6)
	v_mfma_f32_32x32x16_bf16 v[32:47], v[214:217], v[218:221], v[32:47]
	s_waitcnt lgkmcnt(4)
	v_mfma_f32_32x32x16_bf16 v[32:47], v[222:225], v[226:229], v[32:47]
	s_waitcnt lgkmcnt(2)
	v_mfma_f32_32x32x16_bf16 v[32:47], v[240:243], v[244:247], v[32:47]
	s_waitcnt lgkmcnt(0)
	v_mfma_f32_32x32x16_bf16 v[32:47], v[248:251], v[252:255], v[32:47]
	s_nop 11
	v_add_f32_e32 v236, v16, v32
	v_cvt_pk_bf16_f32 v236, v236, s0
	v_lshl_add_u64 v[226:227], s[98:99], 0, v[152:153]
	global_store_short v[226:227], v236, off
	v_add_f32_e32 v237, v17, v33
	v_cvt_pk_bf16_f32 v237, v237, s0
	v_lshl_add_u64 v[228:229], s[98:99], 0, v[154:155]
	global_store_short v[228:229], v237, off
	v_add_f32_e32 v236, v18, v34
	v_cvt_pk_bf16_f32 v236, v236, s0
	v_lshl_add_u64 v[226:227], s[98:99], 0, v[156:157]
	global_store_short v[226:227], v236, off
	v_add_f32_e32 v237, v19, v35
	v_cvt_pk_bf16_f32 v237, v237, s0
	v_lshl_add_u64 v[228:229], s[98:99], 0, v[158:159]
	global_store_short v[228:229], v237, off
	v_add_f32_e32 v236, v20, v36
	v_cvt_pk_bf16_f32 v236, v236, s0
	v_lshl_add_u64 v[226:227], s[98:99], 0, v[160:161]
	global_store_short v[226:227], v236, off
	v_add_f32_e32 v237, v21, v37
	v_cvt_pk_bf16_f32 v237, v237, s0
	v_lshl_add_u64 v[228:229], s[98:99], 0, v[162:163]
	global_store_short v[228:229], v237, off
	v_add_f32_e32 v236, v22, v38
	v_cvt_pk_bf16_f32 v236, v236, s0
	v_lshl_add_u64 v[226:227], s[98:99], 0, v[164:165]
	global_store_short v[226:227], v236, off
	v_add_f32_e32 v237, v23, v39
	v_cvt_pk_bf16_f32 v237, v237, s0
	v_lshl_add_u64 v[228:229], s[98:99], 0, v[166:167]
	global_store_short v[228:229], v237, off
	v_add_f32_e32 v236, v24, v40
	v_cvt_pk_bf16_f32 v236, v236, s0
	v_lshl_add_u64 v[226:227], s[98:99], 0, v[168:169]
	global_store_short v[226:227], v236, off
	v_add_f32_e32 v237, v25, v41
	v_cvt_pk_bf16_f32 v237, v237, s0
	v_lshl_add_u64 v[228:229], s[98:99], 0, v[170:171]
	global_store_short v[228:229], v237, off
	v_add_f32_e32 v236, v26, v42
	v_cvt_pk_bf16_f32 v236, v236, s0
	v_lshl_add_u64 v[226:227], s[98:99], 0, v[172:173]
	global_store_short v[226:227], v236, off
	v_add_f32_e32 v237, v27, v43
	v_cvt_pk_bf16_f32 v237, v237, s0
	v_lshl_add_u64 v[228:229], s[98:99], 0, v[174:175]
	global_store_short v[228:229], v237, off
	v_add_f32_e32 v236, v28, v44
	v_cvt_pk_bf16_f32 v236, v236, s0
	v_lshl_add_u64 v[226:227], s[98:99], 0, v[176:177]
	global_store_short v[226:227], v236, off
	v_add_f32_e32 v237, v29, v45
	v_cvt_pk_bf16_f32 v237, v237, s0
	v_lshl_add_u64 v[228:229], s[98:99], 0, v[178:179]
	global_store_short v[228:229], v237, off
	v_add_f32_e32 v236, v30, v46
	v_cvt_pk_bf16_f32 v236, v236, s0
	v_lshl_add_u64 v[226:227], s[98:99], 0, v[180:181]
	global_store_short v[226:227], v236, off
	v_add_f32_e32 v237, v31, v47
	v_cvt_pk_bf16_f32 v237, v237, s0
	v_lshl_add_u64 v[228:229], s[98:99], 0, v[182:183]
	global_store_short v[228:229], v237, off

.Lsw4_join:
	ds_write_b16 v144, v136 offset:62464
	ds_write_b16_d16_hi v144, v136 offset:62608
	ds_write_b16 v144, v137 offset:62752
	ds_write_b16_d16_hi v144, v137 offset:62896
	ds_write_b16 v144, v138 offset:63040
	ds_write_b16_d16_hi v144, v138 offset:63184
	ds_write_b16 v144, v139 offset:63328
	ds_write_b16_d16_hi v144, v139 offset:63472
	s_and_saveexec_b64 s[52:53], s[0:1]
	ds_write_b32 v205, v201
	s_or_b64 exec, exec, s[52:53]
	s_waitcnt lgkmcnt(0)
	s_barrier
	s_and_saveexec_b64 s[52:53], s[4:5]
	s_cbranch_execz .LBB0_886
	s_add_i32 s10, s79, 0xfffffec0
	s_add_i32 s81, s80, 0x140
	s_and_b64 s[84:85], s[48:49], exec
	s_cselect_b32 s10, s10, s81
	s_add_u32 s84, s46, s10
	s_addc_u32 s85, 0, s47
	s_lshl_b64 s[98:99], s[84:85], 11
	ds_read_b128 v[214:217], v209 offset:53248
	ds_read_b128 v[218:221], v210 offset:62464
	ds_read_b128 v[222:225], v209 offset:53280
	ds_read_b128 v[226:229], v210 offset:62496
	ds_read_b128 v[240:243], v209 offset:53312
	ds_read_b128 v[244:247], v210 offset:62528
	ds_read_b128 v[248:251], v209 offset:53344
	ds_read_b128 v[252:255], v210 offset:62560
	s_waitcnt lgkmcnt(6)
	v_mfma_f32_32x32x16_bf16 v[16:31], v[214:217], v[218:221], 0
	ds_read_b128 v[214:217], v206 offset:17408
	ds_read_b128 v[218:221], v207
	s_waitcnt lgkmcnt(6)
	v_mfma_f32_32x32x16_bf16 v[16:31], v[222:225], v[226:229], v[16:31]
	ds_read_b128 v[222:225], v206 offset:17440
	ds_read_b128 v[226:229], v207 offset:32
	s_waitcnt lgkmcnt(6)
	v_mfma_f32_32x32x16_bf16 v[16:31], v[240:243], v[244:247], v[16:31]
	ds_read_b128 v[240:243], v206 offset:17472
	ds_read_b128 v[244:247], v207 offset:64
	s_waitcnt lgkmcnt(6)
	v_mfma_f32_32x32x16_bf16 v[16:31], v[248:251], v[252:255], v[16:31]
	ds_read_b128 v[248:251], v206 offset:17504
	ds_read_b128 v[252:255], v207 offset:96
	s_waitcnt lgkmcnt(6)
	v_mfma_f32_32x32x16_bf16 v[32:47], v[214:217], v[218:221], 0
	ds_read_b128 v[214:217], v206 offset:17536
	ds_read_b128 v[218:221], v207 offset:128
	s_waitcnt lgkmcnt(6)
	v_mfma_f32_32x32x16_bf16 v[32:47], v[222:225], v[226:229], v[32:47]
	ds_read_b128 v[222:225], v206 offset:17568
	ds_read_b128 v[226:229], v207 offset:160
	s_waitcnt lgkmcnt(6)
	v_mfma_f32_32x32x16_bf16 v[32:47], v[240:243], v[244:247], v[32:47]
	ds_read_b128 v[240:243], v206 offset:17600
	ds_read_b128 v[244:247], v207 offset:192
	s_waitcnt lgkmcnt(6)
	v_mfma_f32_32x32x16_bf16 v[32:47], v[248:251], v[252:255], v[32:47]
	ds_read_b128 v[248:251], v206 offset:17632
	ds_read_b128 v[252:255], v207 offset:224
	s_waitcnt lgkmcnt(6)
	v_mfma_f32_32x32x16_bf16 v[32:47], v[214:217], v[218:221], v[32:47]
	s_waitcnt lgkmcnt(4)
	v_mfma_f32_32x32x16_bf16 v[32:47], v[222:225], v[226:229], v[32:47]
	s_waitcnt lgkmcnt(2)
	v_mfma_f32_32x32x16_bf16 v[32:47], v[240:243], v[244:247], v[32:47]
	s_waitcnt lgkmcnt(0)
	v_mfma_f32_32x32x16_bf16 v[32:47], v[248:251], v[252:255], v[32:47]
	s_nop 11
	v_add_f32_e32 v236, v16, v32
	v_cvt_pk_bf16_f32 v236, v236, s0
	v_lshl_add_u64 v[226:227], s[98:99], 0, v[152:153]
	global_store_short v[226:227], v236, off
	v_add_f32_e32 v237, v17, v33
	v_cvt_pk_bf16_f32 v237, v237, s0
	v_lshl_add_u64 v[228:229], s[98:99], 0, v[154:155]
	global_store_short v[228:229], v237, off
	v_add_f32_e32 v236, v18, v34
	v_cvt_pk_bf16_f32 v236, v236, s0
	v_lshl_add_u64 v[226:227], s[98:99], 0, v[156:157]
	global_store_short v[226:227], v236, off
	v_add_f32_e32 v237, v19, v35
	v_cvt_pk_bf16_f32 v237, v237, s0
	v_lshl_add_u64 v[228:229], s[98:99], 0, v[158:159]
	global_store_short v[228:229], v237, off
	v_add_f32_e32 v236, v20, v36
	v_cvt_pk_bf16_f32 v236, v236, s0
	v_lshl_add_u64 v[226:227], s[98:99], 0, v[160:161]
	global_store_short v[226:227], v236, off
	v_add_f32_e32 v237, v21, v37
	v_cvt_pk_bf16_f32 v237, v237, s0
	v_lshl_add_u64 v[228:229], s[98:99], 0, v[162:163]
	global_store_short v[228:229], v237, off
	v_add_f32_e32 v236, v22, v38
	v_cvt_pk_bf16_f32 v236, v236, s0
	v_lshl_add_u64 v[226:227], s[98:99], 0, v[164:165]
	global_store_short v[226:227], v236, off
	v_add_f32_e32 v237, v23, v39
	v_cvt_pk_bf16_f32 v237, v237, s0
	v_lshl_add_u64 v[228:229], s[98:99], 0, v[166:167]
	global_store_short v[228:229], v237, off
	v_add_f32_e32 v236, v24, v40
	v_cvt_pk_bf16_f32 v236, v236, s0
	v_lshl_add_u64 v[226:227], s[98:99], 0, v[168:169]
	global_store_short v[226:227], v236, off
	v_add_f32_e32 v237, v25, v41
	v_cvt_pk_bf16_f32 v237, v237, s0
	v_lshl_add_u64 v[228:229], s[98:99], 0, v[170:171]
	global_store_short v[228:229], v237, off
	v_add_f32_e32 v236, v26, v42
	v_cvt_pk_bf16_f32 v236, v236, s0
	v_lshl_add_u64 v[226:227], s[98:99], 0, v[172:173]
	global_store_short v[226:227], v236, off
	v_add_f32_e32 v237, v27, v43
	v_cvt_pk_bf16_f32 v237, v237, s0
	v_lshl_add_u64 v[228:229], s[98:99], 0, v[174:175]
	global_store_short v[228:229], v237, off
	v_add_f32_e32 v236, v28, v44
	v_cvt_pk_bf16_f32 v236, v236, s0
	v_lshl_add_u64 v[226:227], s[98:99], 0, v[176:177]
	global_store_short v[226:227], v236, off
	v_add_f32_e32 v237, v29, v45
	v_cvt_pk_bf16_f32 v237, v237, s0
	v_lshl_add_u64 v[228:229], s[98:99], 0, v[178:179]
	global_store_short v[228:229], v237, off
	v_add_f32_e32 v236, v30, v46
	v_cvt_pk_bf16_f32 v236, v236, s0
	v_lshl_add_u64 v[226:227], s[98:99], 0, v[180:181]
	global_store_short v[226:227], v236, off
	v_add_f32_e32 v237, v31, v47
	v_cvt_pk_bf16_f32 v237, v237, s0
	v_lshl_add_u64 v[228:229], s[98:99], 0, v[182:183]
	global_store_short v[228:229], v237, off

.Lsw5_join:
	ds_write_b16 v144, v140 offset:62464
	ds_write_b16_d16_hi v144, v140 offset:62608
	ds_write_b16 v144, v141 offset:62752
	ds_write_b16_d16_hi v144, v141 offset:62896
	ds_write_b16 v144, v142 offset:63040
	ds_write_b16_d16_hi v144, v142 offset:63184
	ds_write_b16 v144, v143 offset:63328
	ds_write_b16_d16_hi v144, v143 offset:63472
	s_and_saveexec_b64 s[52:53], s[0:1]
	ds_write_b32 v205, v200
	s_or_b64 exec, exec, s[52:53]
	s_waitcnt lgkmcnt(0)
	s_barrier
	s_and_saveexec_b64 s[52:53], s[4:5]
	s_cbranch_execz .LBB0_894
	s_add_i32 s10, s79, 0xffffff00
	s_add_i32 s81, s80, 0x100
	s_and_b64 s[84:85], s[48:49], exec
	s_cselect_b32 s10, s10, s81
	s_add_u32 s84, s46, s10
	s_addc_u32 s85, 0, s47
	s_lshl_b64 s[98:99], s[84:85], 11
	ds_read_b128 v[214:217], v209 offset:53248
	ds_read_b128 v[218:221], v210 offset:62464
	ds_read_b128 v[222:225], v209 offset:53280
	ds_read_b128 v[226:229], v210 offset:62496
	ds_read_b128 v[240:243], v209 offset:53312
	ds_read_b128 v[244:247], v210 offset:62528
	ds_read_b128 v[248:251], v209 offset:53344
	ds_read_b128 v[252:255], v210 offset:62560
	s_waitcnt lgkmcnt(6)
	v_mfma_f32_32x32x16_bf16 v[16:31], v[214:217], v[218:221], 0
	ds_read_b128 v[214:217], v206 offset:17408
	ds_read_b128 v[218:221], v207
	s_waitcnt lgkmcnt(6)
	v_mfma_f32_32x32x16_bf16 v[16:31], v[222:225], v[226:229], v[16:31]
	ds_read_b128 v[222:225], v206 offset:17440
	ds_read_b128 v[226:229], v207 offset:32
	s_waitcnt lgkmcnt(6)
	v_mfma_f32_32x32x16_bf16 v[16:31], v[240:243], v[244:247], v[16:31]
	ds_read_b128 v[240:243], v206 offset:17472
	ds_read_b128 v[244:247], v207 offset:64
	s_waitcnt lgkmcnt(6)
	v_mfma_f32_32x32x16_bf16 v[16:31], v[248:251], v[252:255], v[16:31]
	ds_read_b128 v[248:251], v206 offset:17504
	ds_read_b128 v[252:255], v207 offset:96
	s_waitcnt lgkmcnt(6)
	v_mfma_f32_32x32x16_bf16 v[32:47], v[214:217], v[218:221], 0
	ds_read_b128 v[214:217], v206 offset:17536
	ds_read_b128 v[218:221], v207 offset:128
	s_waitcnt lgkmcnt(6)
	v_mfma_f32_32x32x16_bf16 v[32:47], v[222:225], v[226:229], v[32:47]
	ds_read_b128 v[222:225], v206 offset:17568
	ds_read_b128 v[226:229], v207 offset:160
	s_waitcnt lgkmcnt(6)
	v_mfma_f32_32x32x16_bf16 v[32:47], v[240:243], v[244:247], v[32:47]
	ds_read_b128 v[240:243], v206 offset:17600
	ds_read_b128 v[244:247], v207 offset:192
	s_waitcnt lgkmcnt(6)
	v_mfma_f32_32x32x16_bf16 v[32:47], v[248:251], v[252:255], v[32:47]
	ds_read_b128 v[248:251], v206 offset:17632
	ds_read_b128 v[252:255], v207 offset:224
	s_waitcnt lgkmcnt(6)
	v_mfma_f32_32x32x16_bf16 v[32:47], v[214:217], v[218:221], v[32:47]
	s_waitcnt lgkmcnt(4)
	v_mfma_f32_32x32x16_bf16 v[32:47], v[222:225], v[226:229], v[32:47]
	s_waitcnt lgkmcnt(2)
	v_mfma_f32_32x32x16_bf16 v[32:47], v[240:243], v[244:247], v[32:47]
	s_waitcnt lgkmcnt(0)
	v_mfma_f32_32x32x16_bf16 v[32:47], v[248:251], v[252:255], v[32:47]
	s_nop 11
	v_add_f32_e32 v236, v16, v32
	v_cvt_pk_bf16_f32 v236, v236, s0
	v_lshl_add_u64 v[226:227], s[98:99], 0, v[152:153]
	global_store_short v[226:227], v236, off
	v_add_f32_e32 v237, v17, v33
	v_cvt_pk_bf16_f32 v237, v237, s0
	v_lshl_add_u64 v[228:229], s[98:99], 0, v[154:155]
	global_store_short v[228:229], v237, off
	v_add_f32_e32 v236, v18, v34
	v_cvt_pk_bf16_f32 v236, v236, s0
	v_lshl_add_u64 v[226:227], s[98:99], 0, v[156:157]
	global_store_short v[226:227], v236, off
	v_add_f32_e32 v237, v19, v35
	v_cvt_pk_bf16_f32 v237, v237, s0
	v_lshl_add_u64 v[228:229], s[98:99], 0, v[158:159]
	global_store_short v[228:229], v237, off
	v_add_f32_e32 v236, v20, v36
	v_cvt_pk_bf16_f32 v236, v236, s0
	v_lshl_add_u64 v[226:227], s[98:99], 0, v[160:161]
	global_store_short v[226:227], v236, off
	v_add_f32_e32 v237, v21, v37
	v_cvt_pk_bf16_f32 v237, v237, s0
	v_lshl_add_u64 v[228:229], s[98:99], 0, v[162:163]
	global_store_short v[228:229], v237, off
	v_add_f32_e32 v236, v22, v38
	v_cvt_pk_bf16_f32 v236, v236, s0
	v_lshl_add_u64 v[226:227], s[98:99], 0, v[164:165]
	global_store_short v[226:227], v236, off
	v_add_f32_e32 v237, v23, v39
	v_cvt_pk_bf16_f32 v237, v237, s0
	v_lshl_add_u64 v[228:229], s[98:99], 0, v[166:167]
	global_store_short v[228:229], v237, off
	v_add_f32_e32 v236, v24, v40
	v_cvt_pk_bf16_f32 v236, v236, s0
	v_lshl_add_u64 v[226:227], s[98:99], 0, v[168:169]
	global_store_short v[226:227], v236, off
	v_add_f32_e32 v237, v25, v41
	v_cvt_pk_bf16_f32 v237, v237, s0
	v_lshl_add_u64 v[228:229], s[98:99], 0, v[170:171]
	global_store_short v[228:229], v237, off
	v_add_f32_e32 v236, v26, v42
	v_cvt_pk_bf16_f32 v236, v236, s0
	v_lshl_add_u64 v[226:227], s[98:99], 0, v[172:173]
	global_store_short v[226:227], v236, off
	v_add_f32_e32 v237, v27, v43
	v_cvt_pk_bf16_f32 v237, v237, s0
	v_lshl_add_u64 v[228:229], s[98:99], 0, v[174:175]
	global_store_short v[228:229], v237, off
	v_add_f32_e32 v236, v28, v44
	v_cvt_pk_bf16_f32 v236, v236, s0
	v_lshl_add_u64 v[226:227], s[98:99], 0, v[176:177]
	global_store_short v[226:227], v236, off
	v_add_f32_e32 v237, v29, v45
	v_cvt_pk_bf16_f32 v237, v237, s0
	v_lshl_add_u64 v[228:229], s[98:99], 0, v[178:179]
	global_store_short v[228:229], v237, off
	v_add_f32_e32 v236, v30, v46
	v_cvt_pk_bf16_f32 v236, v236, s0
	v_lshl_add_u64 v[226:227], s[98:99], 0, v[180:181]
	global_store_short v[226:227], v236, off
	v_add_f32_e32 v237, v31, v47
	v_cvt_pk_bf16_f32 v237, v237, s0
	v_lshl_add_u64 v[228:229], s[98:99], 0, v[182:183]
	global_store_short v[228:229], v237, off

	.amdhsa_kernel _Z10hybrid_fwd5KArgs
		.amdhsa_group_segment_fixed_size 0
		.amdhsa_private_segment_fixed_size 0
		.amdhsa_kernarg_size 408
		.amdhsa_user_sgpr_count 2
		.amdhsa_user_sgpr_dispatch_ptr 0
		.amdhsa_user_sgpr_queue_ptr 0
		.amdhsa_user_sgpr_kernarg_segment_ptr 1
		.amdhsa_user_sgpr_dispatch_id 0
		.amdhsa_user_sgpr_kernarg_preload_length 0
		.amdhsa_user_sgpr_kernarg_preload_offset 0
		.amdhsa_user_sgpr_private_segment_size 0
		.amdhsa_uses_dynamic_stack 0
		.amdhsa_enable_private_segment 0
		.amdhsa_system_sgpr_workgroup_id_x 1
		.amdhsa_system_sgpr_workgroup_id_y 0
		.amdhsa_system_sgpr_workgroup_id_z 0
		.amdhsa_system_sgpr_workgroup_info 0
		.amdhsa_system_vgpr_workitem_id 2
		.amdhsa_next_free_vgpr 256
		.amdhsa_next_free_sgpr 102
		.amdhsa_accum_offset 256
		.amdhsa_reserve_vcc 1
		.amdhsa_float_round_mode_32 0
		.amdhsa_float_round_mode_16_64 0
		.amdhsa_float_denorm_mode_32 3
		.amdhsa_float_denorm_mode_16_64 3
		.amdhsa_dx10_clamp 1
		.amdhsa_ieee_mode 1
		.amdhsa_fp16_overflow 0
		.amdhsa_tg_split 0
		.amdhsa_exception_fp_ieee_invalid_op 0
		.amdhsa_exception_fp_denorm_src 0
		.amdhsa_exception_fp_ieee_div_zero 0
		.amdhsa_exception_fp_ieee_overflow 0
		.amdhsa_exception_fp_ieee_underflow 0
		.amdhsa_exception_fp_ieee_inexact 0
		.amdhsa_exception_int_div_zero 0
	.end_amdhsa_kernel

amdhsa.kernels:
  - .agpr_count:     0
    .args:
      - .offset:         0
        .size:           152
        .value_kind:     by_value
      - .offset:         152
        .size:           4
        .value_kind:     hidden_block_count_x
      - .offset:         156
        .size:           4
        .value_kind:     hidden_block_count_y
      - .offset:         160
        .size:           4
        .value_kind:     hidden_block_count_z
      - .offset:         164
        .size:           2
        .value_kind:     hidden_group_size_x
      - .offset:         166
        .size:           2
        .value_kind:     hidden_group_size_y
      - .offset:         168
        .size:           2
        .value_kind:     hidden_group_size_z
      - .offset:         170
        .size:           2
        .value_kind:     hidden_remainder_x
      - .offset:         172
        .size:           2
        .value_kind:     hidden_remainder_y
      - .offset:         174
        .size:           2
        .value_kind:     hidden_remainder_z
      - .offset:         192
        .size:           8
        .value_kind:     hidden_global_offset_x
      - .offset:         200
        .size:           8
        .value_kind:     hidden_global_offset_y
      - .offset:         208
        .size:           8
        .value_kind:     hidden_global_offset_z
      - .offset:         216
        .size:           2
        .value_kind:     hidden_grid_dims
      - .offset:         240
        .size:           8
        .value_kind:     hidden_multigrid_sync_arg
      - .offset:         272
        .size:           4
        .value_kind:     hidden_dynamic_lds_size
    .group_segment_fixed_size: 0
    .kernarg_segment_align: 8
    .kernarg_segment_size: 408
    .language:       OpenCL C
    .language_version:
      - 2
      - 0
    .max_flat_workgroup_size: 512
    .name:           _Z10hybrid_fwd5KArgs
    .private_segment_fixed_size: 0
    .sgpr_count:     108
    .sgpr_spill_count: 49
    .symbol:         _Z10hybrid_fwd5KArgs.kd
    .uniform_work_group_size: 1
    .uses_dynamic_stack: false
    .vgpr_count:     256
    .vgpr_spill_count: 0
    .wavefront_size: 64
